# combined variant with the redundant s_nop 10 in front of the GQA exp2 blocks shortened (V reads already give the MFMA to VALU distance)
# speedup vs baseline: 1.0023x; 1.0023x over previous
.LBB0_580:
	ds_read_b128 v[32:35], v194
	ds_read_b128 v[36:39], v194 offset:4608
	ds_read_b128 v[96:99], v194 offset:32
	ds_read_b128 v[104:107], v194 offset:4640
	s_waitcnt lgkmcnt(3)
	v_mfma_f32_32x32x16_bf16 v[48:63], v[32:35], v[64:67], 0
	s_add_i32 s15, s14, 1
	s_cmp_ge_u32 s15, s37
	ds_read_b128 v[114:117], v194 offset:64
	s_waitcnt lgkmcnt(3)
	v_mfma_f32_32x32x16_bf16 v[32:47], v[36:39], v[64:67], 0
	ds_read_b128 v[122:125], v194 offset:4672
	s_waitcnt lgkmcnt(3)
	v_mfma_f32_32x32x16_bf16 v[48:63], v[96:99], v[68:71], v[48:63]
	ds_read_b128 v[118:121], v194 offset:96
	s_waitcnt lgkmcnt(3)
	v_mfma_f32_32x32x16_bf16 v[32:47], v[104:107], v[68:71], v[32:47]
	ds_read_b128 v[134:137], v194 offset:4704
	s_waitcnt lgkmcnt(3)
	v_mfma_f32_32x32x16_bf16 v[48:63], v[114:117], v[72:75], v[48:63]
	ds_read_b64_tr_b16 v[138:139], v218 offset:9216
	ds_read_b64_tr_b16 v[140:141], v218 offset:10240
	s_waitcnt lgkmcnt(4)
	v_mfma_f32_32x32x16_bf16 v[32:47], v[122:125], v[72:75], v[32:47]
	ds_read_b64_tr_b16 v[148:149], v218 offset:10496
	ds_read_b64_tr_b16 v[146:147], v218 offset:9472
	s_waitcnt lgkmcnt(5)
	v_mfma_f32_32x32x16_bf16 v[48:63], v[118:121], v[76:79], v[48:63]
	ds_read_b64_tr_b16 v[152:153], v218 offset:11264
	ds_read_b64_tr_b16 v[154:155], v218 offset:12288
	s_waitcnt lgkmcnt(6)
	v_mfma_f32_32x32x16_bf16 v[32:47], v[134:137], v[76:79], v[32:47]
	ds_read_b64_tr_b16 v[158:159], v218 offset:12544
	ds_read_b64_tr_b16 v[156:157], v218 offset:11520
	ds_read_b64_tr_b16 v[160:161], v218 offset:13312
	ds_read_b64_tr_b16 v[162:163], v218 offset:14336
	ds_read_b64_tr_b16 v[166:167], v218 offset:14592
	ds_read_b64_tr_b16 v[164:165], v218 offset:13568
	ds_read_b64_tr_b16 v[168:169], v218 offset:15360
	ds_read_b64_tr_b16 v[170:171], v218 offset:16384
	ds_read_b64_tr_b16 v[174:175], v218 offset:16640
	ds_read_b64_tr_b16 v[172:173], v218 offset:15616
	s_nop 1
	v_exp_f32_e32 v96, v48
	v_exp_f32_e32 v97, v49
	v_exp_f32_e32 v98, v50
	v_exp_f32_e32 v99, v51
	v_exp_f32_e32 v104, v52
	v_exp_f32_e32 v105, v53
	v_exp_f32_e32 v106, v54
	v_exp_f32_e32 v109, v32
	v_exp_f32_e32 v110, v33
	v_exp_f32_e32 v111, v34
	v_exp_f32_e32 v114, v35
	v_exp_f32_e32 v107, v55
	v_cvt_pk_bf16_f32 v32, v96, v97
	v_cvt_pk_bf16_f32 v33, v98, v99
	v_cvt_pk_bf16_f32 v34, v104, v105
	v_cvt_pk_bf16_f32 v35, v106, v107
	v_exp_f32_e32 v115, v36
	s_waitcnt lgkmcnt(14)
	v_mfma_f32_32x32x16_bf16 v[0:15], v[138:141], v[32:35], v[0:15]
	v_exp_f32_e32 v116, v37
	v_exp_f32_e32 v117, v38
	v_exp_f32_e32 v118, v39
	v_exp_f32_e32 v119, v56
	v_exp_f32_e32 v120, v57
	v_exp_f32_e32 v126, v58
	v_exp_f32_e32 v125, v59
	s_waitcnt lgkmcnt(12)
	v_mfma_f32_32x32x16_bf16 v[16:31], v[146:149], v[32:35], v[16:31]
	v_exp_f32_e32 v124, v60
	v_exp_f32_e32 v123, v61
	v_exp_f32_e32 v122, v62
	v_exp_f32_e32 v121, v63
	v_cvt_pk_bf16_f32 v36, v109, v110
	v_cvt_pk_bf16_f32 v37, v111, v114
	v_cvt_pk_bf16_f32 v38, v115, v116
	v_cvt_pk_bf16_f32 v39, v117, v118
	v_cvt_pk_bf16_f32 v32, v119, v120
	v_cvt_pk_bf16_f32 v33, v126, v125
	v_cvt_pk_bf16_f32 v34, v124, v123
	v_cvt_pk_bf16_f32 v35, v122, v121
	v_exp_f32_e32 v138, v40
	s_waitcnt lgkmcnt(10)
	v_mfma_f32_32x32x16_bf16 v[0:15], v[152:155], v[32:35], v[0:15]
	v_exp_f32_e32 v137, v41
	v_exp_f32_e32 v136, v42
	v_exp_f32_e32 v134, v43
	v_exp_f32_e32 v131, v44
	v_exp_f32_e32 v135, v45
	v_exp_f32_e32 v133, v46
	v_exp_f32_e32 v127, v47
	s_waitcnt lgkmcnt(8)
	v_mfma_f32_32x32x16_bf16 v[16:31], v[156:159], v[32:35], v[16:31]
	v_cvt_pk_bf16_f32 v32, v138, v137
	v_cvt_pk_bf16_f32 v33, v136, v134
	v_cvt_pk_bf16_f32 v34, v131, v135
	v_cvt_pk_bf16_f32 v35, v133, v127
	s_waitcnt lgkmcnt(6)
	v_mfma_f32_32x32x16_bf16 v[0:15], v[160:163], v[36:39], v[0:15]
	s_waitcnt lgkmcnt(4)
	v_mfma_f32_32x32x16_bf16 v[16:31], v[164:167], v[36:39], v[16:31]
	s_waitcnt lgkmcnt(2)
	v_mfma_f32_32x32x16_bf16 v[0:15], v[168:171], v[32:35], v[0:15]
	s_waitcnt lgkmcnt(0)
	v_mfma_f32_32x32x16_bf16 v[16:31], v[172:175], v[32:35], v[16:31]
	s_cbranch_scc1 .LBB0_582
	s_cmp_ge_u32 s13, s37
	s_cbranch_scc1 .Lgqa_w0_tail
	s_waitcnt vmcnt(3)
	ds_write_b128 v193, v[88:91] offset:17408
	s_waitcnt vmcnt(2)
	ds_write_b128 v219, v[92:95] offset:26624
	s_branch .LBB0_582

.LBB0_584:
	ds_read_b128 v[32:35], v194 offset:17408
	ds_read_b128 v[36:39], v194 offset:22016
	ds_read_b128 v[140:143], v194 offset:17440
	ds_read_b128 v[146:149], v194 offset:22048
	s_waitcnt lgkmcnt(3)
	v_mfma_f32_32x32x16_bf16 v[48:63], v[32:35], v[64:67], 0
	v_add_f32_e32 v222, v96, v97
	v_add_f32_e32 v223, v109, v110
	v_add_f32_e32 v222, v98, v222
	v_add_f32_e32 v223, v111, v223
	s_andn2_b64 vcc, exec, s[10:11]
	ds_read_b128 v[152:155], v194 offset:17472
	s_waitcnt lgkmcnt(3)
	v_mfma_f32_32x32x16_bf16 v[32:47], v[36:39], v[64:67], 0
	v_add_f32_e32 v222, v99, v222
	v_add_f32_e32 v223, v114, v223
	v_add_f32_e32 v222, v104, v222
	v_add_f32_e32 v223, v115, v223
	ds_read_b128 v[160:163], v194 offset:22080
	s_waitcnt lgkmcnt(3)
	v_mfma_f32_32x32x16_bf16 v[48:63], v[140:143], v[68:71], v[48:63]
	v_add_f32_e32 v222, v105, v222
	v_add_f32_e32 v223, v116, v223
	v_add_f32_e32 v222, v106, v222
	v_add_f32_e32 v223, v117, v223
	ds_read_b128 v[156:159], v194 offset:17504
	s_waitcnt lgkmcnt(3)
	v_mfma_f32_32x32x16_bf16 v[32:47], v[146:149], v[68:71], v[32:47]
	v_add_f32_e32 v222, v107, v222
	v_add_f32_e32 v223, v118, v223
	v_add_f32_e32 v222, v119, v222
	v_add_f32_e32 v223, v138, v223
	ds_read_b128 v[164:167], v194 offset:22112
	s_waitcnt lgkmcnt(3)
	v_mfma_f32_32x32x16_bf16 v[48:63], v[152:155], v[72:75], v[48:63]
	v_add_f32_e32 v222, v120, v222
	v_add_f32_e32 v223, v137, v223
	v_add_f32_e32 v222, v126, v222
	v_add_f32_e32 v223, v136, v223
	ds_read_b64_tr_b16 v[168:169], v218 offset:26624
	ds_read_b64_tr_b16 v[170:171], v218 offset:27648
	s_waitcnt lgkmcnt(4)
	v_mfma_f32_32x32x16_bf16 v[32:47], v[160:163], v[72:75], v[32:47]
	v_add_f32_e32 v222, v125, v222
	v_add_f32_e32 v223, v134, v223
	v_add_f32_e32 v222, v124, v222
	v_add_f32_e32 v223, v131, v223
	ds_read_b64_tr_b16 v[174:175], v218 offset:27904
	ds_read_b64_tr_b16 v[172:173], v218 offset:26880
	s_waitcnt lgkmcnt(5)
	v_mfma_f32_32x32x16_bf16 v[48:63], v[156:159], v[76:79], v[48:63]
	v_add_f32_e32 v222, v123, v222
	v_add_f32_e32 v223, v135, v223
	v_add_f32_e32 v222, v122, v222
	v_add_f32_e32 v223, v133, v223
	ds_read_b64_tr_b16 v[176:177], v218 offset:28672
	ds_read_b64_tr_b16 v[178:179], v218 offset:29696
	s_waitcnt lgkmcnt(6)
	v_mfma_f32_32x32x16_bf16 v[32:47], v[164:167], v[76:79], v[32:47]
	ds_read_b64_tr_b16 v[182:183], v218 offset:29952
	ds_read_b64_tr_b16 v[180:181], v218 offset:28928
	ds_read_b64_tr_b16 v[184:185], v218 offset:30720
	ds_read_b64_tr_b16 v[186:187], v218 offset:31744
	ds_read_b64_tr_b16 v[190:191], v218 offset:32000
	ds_read_b64_tr_b16 v[188:189], v218 offset:30976
	ds_read_b64_tr_b16 v[196:197], v218 offset:32768
	ds_read_b64_tr_b16 v[198:199], v218 offset:33792
	ds_read_b64_tr_b16 v[202:203], v218 offset:34048
	ds_read_b64_tr_b16 v[200:201], v218 offset:33024
	v_add_f32_e32 v222, v121, v222
	v_add_f32_e32 v223, v127, v223
	v_add_f32_e32 v222, v222, v223
	s_nop 1
	v_exp_f32_e32 v48, v48
	v_exp_f32_e32 v141, v58
	v_exp_f32_e32 v140, v59
	v_exp_f32_e32 v60, v60
	v_exp_f32_e32 v59, v61
	v_exp_f32_e32 v58, v62
	v_exp_f32_e32 v139, v32
	v_exp_f32_e32 v32, v49
	v_exp_f32_e32 v49, v33
	v_exp_f32_e32 v33, v50
	v_exp_f32_e32 v50, v34
	v_exp_f32_e32 v34, v51
	v_exp_f32_e32 v51, v35
	v_exp_f32_e32 v35, v52
	v_exp_f32_e32 v52, v36
	v_exp_f32_e32 v36, v53
	v_exp_f32_e32 v53, v37
	v_exp_f32_e32 v37, v54
	v_exp_f32_e32 v54, v38
	v_exp_f32_e32 v38, v55
	v_cvt_pk_bf16_f32 v146, v48, v32
	v_cvt_pk_bf16_f32 v147, v33, v34
	v_cvt_pk_bf16_f32 v148, v35, v36
	v_cvt_pk_bf16_f32 v149, v37, v38
	v_exp_f32_e32 v39, v39
	s_waitcnt lgkmcnt(14)
	v_mfma_f32_32x32x16_bf16 v[0:15], v[168:171], v[146:149], v[0:15]
	v_exp_f32_e32 v55, v56
	v_exp_f32_e32 v56, v57
	v_exp_f32_e32 v57, v63
	v_cvt_pk_bf16_f32 v152, v139, v49
	v_cvt_pk_bf16_f32 v153, v50, v51
	v_cvt_pk_bf16_f32 v154, v52, v53
	v_cvt_pk_bf16_f32 v155, v54, v39
	s_waitcnt lgkmcnt(12)
	v_mfma_f32_32x32x16_bf16 v[16:31], v[172:175], v[146:149], v[16:31]
	v_cvt_pk_bf16_f32 v146, v55, v56
	v_cvt_pk_bf16_f32 v147, v141, v140
	v_cvt_pk_bf16_f32 v148, v60, v59
	v_cvt_pk_bf16_f32 v149, v58, v57
	v_exp_f32_e32 v63, v40
	v_exp_f32_e32 v62, v41
	v_exp_f32_e32 v61, v42
	s_waitcnt lgkmcnt(10)
	v_mfma_f32_32x32x16_bf16 v[0:15], v[176:179], v[146:149], v[0:15]
	v_exp_f32_e32 v43, v43
	v_exp_f32_e32 v41, v44
	v_exp_f32_e32 v44, v45
	v_exp_f32_e32 v42, v46
	v_exp_f32_e32 v40, v47
	s_waitcnt lgkmcnt(8)
	v_mfma_f32_32x32x16_bf16 v[16:31], v[180:183], v[146:149], v[16:31]
	v_add_f32_e32 v224, v48, v32
	v_add_f32_e32 v225, v139, v49
	v_add_f32_e32 v224, v33, v224
	v_add_f32_e32 v225, v50, v225
	v_add_f32_e32 v224, v34, v224
	v_add_f32_e32 v225, v51, v225
	v_add_f32_e32 v224, v35, v224
	v_add_f32_e32 v225, v52, v225
	v_cvt_pk_bf16_f32 v146, v63, v62
	v_cvt_pk_bf16_f32 v147, v61, v43
	v_cvt_pk_bf16_f32 v148, v41, v44
	v_cvt_pk_bf16_f32 v149, v42, v40
	s_waitcnt lgkmcnt(6)
	v_mfma_f32_32x32x16_bf16 v[0:15], v[184:187], v[152:155], v[0:15]
	v_add_f32_e32 v224, v36, v224
	v_add_f32_e32 v225, v53, v225
	v_add_f32_e32 v224, v37, v224
	v_add_f32_e32 v225, v54, v225
	v_add_f32_e32 v224, v38, v224
	v_add_f32_e32 v225, v39, v225
	v_add_f32_e32 v224, v55, v224
	v_add_f32_e32 v225, v63, v225
	s_waitcnt lgkmcnt(4)
	v_mfma_f32_32x32x16_bf16 v[16:31], v[188:191], v[152:155], v[16:31]
	v_add_f32_e32 v224, v56, v224
	v_add_f32_e32 v225, v62, v225
	v_add_f32_e32 v224, v141, v224
	v_add_f32_e32 v225, v61, v225
	v_add_f32_e32 v224, v140, v224
	v_add_f32_e32 v225, v43, v225
	v_add_f32_e32 v224, v60, v224
	v_add_f32_e32 v225, v41, v225
	s_waitcnt lgkmcnt(2)
	v_mfma_f32_32x32x16_bf16 v[0:15], v[196:199], v[146:149], v[0:15]
	v_add_f32_e32 v224, v59, v224
	v_add_f32_e32 v225, v44, v225
	v_add_f32_e32 v224, v58, v224
	v_add_f32_e32 v225, v42, v225
	v_add_f32_e32 v224, v57, v224
	v_add_f32_e32 v225, v40, v225
	v_add_f32_e32 v224, v224, v225
	s_waitcnt lgkmcnt(0)
	v_mfma_f32_32x32x16_bf16 v[16:31], v[200:203], v[146:149], v[16:31]
	s_cbranch_vccnz .LBB0_586
	s_cmp_ge_u32 s14, s12
	s_cbranch_scc1 .Lgqa_w1_tail
	s_waitcnt vmcnt(3)
	ds_write_b128 v193, v[80:83]
	s_waitcnt vmcnt(2)
	ds_write_b128 v219, v[84:87] offset:9216
	s_branch .LBB0_586
